# swa_attn unit prologue: 8 K/V staging loads issued back to back with counted waits, on top of the LayerNorm load/wait restructuring
# baseline (speedup 1.0000x reference)
.LBB0_1381:
	s_bfe_u32 s0, s28, 0x60002
	s_lshl_b32 s2, s28, 5
	s_and_b32 s7, s2, 0xffffe000
	s_lshl_b32 s2, s0, 7
	s_or_b32 s2, s2, s7
	s_add_i32 s12, s2, 0xffffff80
	v_add_u32_e32 v0, s12, v103
	s_and_b32 s3, s28, 3
	v_max_i32_e32 v0, s7, v0
	v_mov_b64_e32 v[4:5], s[20:21]
	s_movk_i32 s22, 0x1400
	v_mad_i64_i32 v[0:1], s[8:9], v0, s22, v[4:5]
	s_lshl_b32 s10, s3, 7
	v_lshl_add_u64 v[0:1], v[0:1], 0, s[10:11]
	v_lshl_add_u64 v[0:1], v[0:1], 0, v[224:225]
	s_movk_i32 s13, 0x1000
	v_add_co_u32_e32 v0, vcc, s13, v0
	s_waitcnt vmcnt(0)
	s_nop 0
	v_addc_co_u32_e32 v1, vcc, 0, v1, vcc
	s_barrier
	global_load_dwordx4 v[200:203], v[0:1], off
	s_movk_i32 s33, 0x1400
	s_lshl_b32 s3, s3, 3
	v_add_u32_e32 v0, s12, v125
	v_max_i32_e32 v0, s7, v0
	v_mad_i64_i32 v[0:1], s[8:9], v0, s22, v[4:5]
	v_lshl_add_u64 v[0:1], v[0:1], 0, s[10:11]
	v_lshl_add_u64 v[0:1], v[0:1], 0, v[224:225]
	v_add_co_u32_e32 v0, vcc, s13, v0
	s_nop 1
	v_addc_co_u32_e32 v1, vcc, 0, v1, vcc
	global_load_dwordx4 v[204:207], v[0:1], off
	v_add_u32_e32 v0, s12, v126
	v_max_i32_e32 v0, s7, v0
	v_mad_i64_i32 v[0:1], s[8:9], v0, s22, v[4:5]
	v_lshl_add_u64 v[0:1], v[0:1], 0, s[10:11]
	v_lshl_add_u64 v[0:1], v[0:1], 0, v[224:225]
	v_add_co_u32_e32 v0, vcc, s13, v0
	s_nop 1
	v_addc_co_u32_e32 v1, vcc, 0, v1, vcc
	global_load_dwordx4 v[208:211], v[0:1], off
	v_add_u32_e32 v0, s12, v127
	v_max_i32_e32 v0, s7, v0
	v_mad_i64_i32 v[0:1], s[8:9], v0, s22, v[4:5]
	v_lshl_add_u64 v[0:1], v[0:1], 0, s[10:11]
	v_lshl_add_u64 v[0:1], v[0:1], 0, v[224:225]
	v_add_co_u32_e32 v0, vcc, s13, v0
	s_nop 1
	v_addc_co_u32_e32 v1, vcc, 0, v1, vcc
	global_load_dwordx4 v[212:215], v[0:1], off
	v_add_u32_e32 v0, s12, v101
	v_max_i32_e32 v0, s7, v0
	v_mad_i64_i32 v[0:1], s[8:9], v0, s22, v[4:5]
	v_lshl_add_u64 v[0:1], v[0:1], 0, s[10:11]
	s_mov_b64 s[8:9], 0x1200
	v_lshl_add_u64 v[4:5], v[0:1], 0, s[8:9]
	v_lshl_add_u64 v[0:1], v[106:107], 1, v[4:5]
	global_load_dwordx4 v[216:219], v[0:1], off
	v_lshl_add_u64 v[0:1], v[108:109], 1, v[4:5]
	global_load_dwordx4 v[220:223], v[0:1], off
	v_lshl_add_u64 v[0:1], v[110:111], 1, v[4:5]
	global_load_dwordx4 v[226:229], v[0:1], off
	v_lshl_add_u64 v[0:1], v[112:113], 1, v[4:5]
	global_load_dwordx4 v[230:233], v[0:1], off
	s_waitcnt vmcnt(7)
	ds_write_b128 v157, v[200:203]
	s_waitcnt vmcnt(6)
	ds_write_b128 v158, v[204:207]
	s_waitcnt vmcnt(5)
	ds_write_b128 v159, v[208:211]
	s_waitcnt vmcnt(4)
	ds_write_b128 v160, v[212:215]
	s_waitcnt vmcnt(3)
	ds_write_b16 v161, v216 offset:36864
	ds_write_b16_d16_hi v161, v216 offset:37392
	ds_write_b16 v161, v217 offset:37920
	ds_write_b16_d16_hi v161, v217 offset:38448
	ds_write_b16 v161, v218 offset:38976
	ds_write_b16_d16_hi v161, v218 offset:39504
	ds_write_b16 v161, v219 offset:40032
	ds_write_b16_d16_hi v162, v219 offset:36864
	s_waitcnt vmcnt(2)
	ds_write_b16 v163, v220 offset:36864
	ds_write_b16_d16_hi v163, v220 offset:37392
	ds_write_b16 v163, v221 offset:37920
	ds_write_b16_d16_hi v163, v221 offset:38448
	ds_write_b16 v163, v222 offset:38976
	ds_write_b16_d16_hi v163, v222 offset:39504
	ds_write_b16 v163, v223 offset:40032
	ds_write_b16_d16_hi v164, v223 offset:36864
	s_waitcnt vmcnt(1)
	ds_write_b16 v165, v226 offset:36864
	ds_write_b16_d16_hi v165, v226 offset:37392
	ds_write_b16 v165, v227 offset:37920
	ds_write_b16_d16_hi v165, v227 offset:38448
	ds_write_b16 v165, v228 offset:38976
	ds_write_b16_d16_hi v165, v228 offset:39504
	ds_write_b16 v165, v229 offset:40032
	ds_write_b16_d16_hi v166, v229 offset:36864
	s_waitcnt vmcnt(0)
	ds_write_b16 v167, v230 offset:36864
	ds_write_b16_d16_hi v167, v230 offset:37392
	ds_write_b16 v167, v231 offset:37920
	ds_write_b16_d16_hi v167, v231 offset:38448
	ds_write_b16 v167, v232 offset:38976
	ds_write_b16_d16_hi v167, v232 offset:39504
	ds_write_b16 v167, v233 offset:40032
	ds_write_b16_d16_hi v168, v233 offset:36864
	s_and_saveexec_b64 s[8:9], s[38:39]
	s_cbranch_execz .LBB0_1389
	global_load_ubyte v0, v[114:115], off
	s_mov_b64 s[22:23], -1
	v_mov_b32_e32 v1, v96
	s_waitcnt vmcnt(0)
	v_lshl_or_b32 v0, v0, 5, s3
	s_and_saveexec_b64 s[12:13], s[66:67]
	s_cbranch_execz .LBB0_1386
	v_mov_b32_e32 v1, v0
	s_mov_b64 s[22:23], 0
	v_mov_b32_e32 v4, v141
	v_mov_b32_e32 v5, v156
	v_mov_b64_e32 v[2:3], v[96:97]
